# scan pass A: the LAB tile stores of item i are issued after the U-tile loads of item i+1 (load latency overlaps the store issue); on top of passC + prologue fixes
# baseline (speedup 1.0000x reference)
.LBB0_394:
	s_or_b64 exec, exec, s[4:5]
	s_andn2_b64 vcc, exec, s[0:1]
	s_mov_b64 s[16:17], 0
	s_waitcnt lgkmcnt(0)
	s_barrier
	s_cbranch_vccnz .LBB0_409
	s_andn2_b64 vcc, exec, s[14:15]
	s_cbranch_vccnz .LBB0_410
	v_readlane_b32 s0, v251, 60
	s_mov_b64 s[4:5], s[70:71]
	v_mov_b32_e32 v4, v194
	v_readlane_b32 s1, v251, 61
	s_andn2_b64 vcc, exec, s[0:1]
	v_readfirstlane_b32 s0, v4
	s_cbranch_vccnz .LBB0_411
	v_mov_b32_e32 v0, s4
	v_add_co_u32_e32 v10, vcc, 0x1000, v0
	v_mov_b32_e32 v0, s5
	s_nop 0
	v_addc_co_u32_e32 v11, vcc, 0, v0, vcc
	flat_load_dwordx4 v[6:9], v[10:11] offset:96
	flat_load_dwordx2 v[12:13], v[10:11] offset:208
	v_mov_b32_e32 v0, s0
	s_movk_i32 s6, 0xffc0
	s_ashr_i32 s1, s0, 6
	v_bfi_b32 v0, s6, v0, v4
	s_mul_i32 s7, s48, 0xfffffa00
	v_bfe_u32 v68, v4, 4, 2
	v_lshlrev_b32_e32 v22, 8, v4
	s_add_u32 s13, s4, 0x400000
	s_mul_i32 s22, s1, 0x4300
	v_lshl_add_u32 v14, s48, 11, v0
	v_and_b32_e32 v17, 0x300, v22
	v_lshlrev_b32_e32 v19, 5, v68
	s_addc_u32 s18, s5, 0
	s_add_i32 s16, s22, 0
	flat_load_dwordx4 v[0:3], v[10:11] offset:152
	flat_load_dwordx2 v[70:71], v[10:11] offset:136
	v_ashrrev_i32_e32 v15, 31, v14
	v_add_u32_e32 v10, 0x400, v14
	v_add_u32_e32 v16, 0x600, v14
	v_add_u32_e32 v18, s7, v14
	v_add3_u32 v26, s16, v17, v19
	v_ashrrev_i32_e32 v11, 31, v10
	v_ashrrev_i32_e32 v17, 31, v16
	v_ashrrev_i32_e32 v19, 31, v18
	v_and_b32_e32 v21, 15, v4
	s_and_b32 s6, s0, 0xffffffc0
	v_and_b32_e32 v20, 63, v4
	v_bfe_u32 v69, v4, 3, 3
	s_ashr_i32 s7, s6, 31
	v_lshlrev_b32_e32 v150, 4, v21
	s_lshl_b32 s19, s48, 1
	v_lshl_add_u32 v25, v69, 8, s16
	v_lshl_add_u32 v75, v20, 2, s16
	s_lshl_b32 s20, s1, 2
	v_and_b32_e32 v5, 7, v4
	v_lshlrev_b32_e32 v4, 10, v4
	v_lshlrev_b32_e32 v24, 5, v5
	v_add_u32_e32 v23, -2, v69
	v_cmp_gt_u32_e64 s[0:1], 16, v20
	v_or_b32_e32 v74, 4, v68
	v_or_b32_e32 v76, 8, v68
	v_or_b32_e32 v78, 12, v68
	v_or_b32_e32 v80, 16, v68
	v_or_b32_e32 v82, 20, v68
	s_waitcnt vmcnt(0)
	v_or_b32_e32 v84, 24, v68
	v_or_b32_e32 v86, 28, v68
	v_or_b32_e32 v88, 32, v68
	v_or_b32_e32 v90, 36, v68
	v_or_b32_e32 v92, 40, v68
	v_or_b32_e32 v94, 44, v68
	v_or_b32_e32 v96, 48, v68
	v_or_b32_e32 v98, 52, v68
	v_or_b32_e32 v100, 56, v68
	v_or_b32_e32 v102, 60, v68
	v_cndmask_b32_e64 v87, 64, v23, s[0:1]
	v_lshlrev_b32_e32 v23, 8, v92
	v_lshlrev_b32_e32 v27, 8, v94
	v_lshlrev_b32_e32 v28, 8, v96
	v_lshlrev_b32_e32 v29, 8, v98
	v_lshlrev_b32_e32 v30, 8, v100
	v_lshlrev_b32_e32 v31, 8, v102
	v_cmp_gt_u32_e32 vcc, 24, v20
	v_or_b32_e32 v89, s6, v21
	v_add_u32_e32 v126, v25, v24
	s_waitcnt lgkmcnt(0)
	v_lshl_add_u64 v[14:15], v[14:15], 2, v[6:7]
	v_lshl_add_u64 v[10:11], v[10:11], 2, v[6:7]
	v_lshl_add_u64 v[6:7], v[16:17], 2, v[6:7]
	v_lshl_add_u64 v[8:9], v[18:19], 2, v[8:9]
	global_load_dword v77, v[14:15], off
	global_load_dword v79, v[14:15], off offset:2048
	global_load_dword v81, v[10:11], off
	global_load_dword v83, v[6:7], off
	global_load_dword v85, v[8:9], off
	v_add_u32_e32 v9, s16, v150
	s_lshl_b64 s[16:17], s[6:7], 1
	v_lshl_add_u64 v[6:7], s[6:7], 2, v[12:13]
	s_add_u32 s16, s4, s16
	v_lshl_add_u64 v[72:73], v[6:7], 0, v[150:151]
	s_addc_u32 s17, s5, s17
	v_lshlrev_b32_e32 v150, 4, v5
	v_and_b32_e32 v7, 0x3000, v4
	v_and_b32_e32 v10, 0x3000, v22
	v_lshl_add_u64 v[4:5], s[16:17], 0, v[150:151]
	s_mov_b64 s[16:17], 0x1d800000
	v_lshlrev_b32_e32 v8, 2, v21
	v_lshl_add_u64 v[104:105], v[4:5], 0, s[16:17]
	v_add_u32_e32 v4, s22, v10
	v_or_b32_e32 v4, v4, v8
	v_lshlrev_b32_e32 v150, 4, v20
	v_lshl_or_b32 v11, v20, 8, v204
	v_add_u32_e32 v91, 0, v4
	v_lshl_add_u64 v[4:5], s[4:5], 0, v[150:151]
	s_mov_b64 s[4:5], 0x300800
	v_lshl_add_u64 v[106:107], v[4:5], 0, s[4:5]
	v_add_u32_e32 v4, s22, v11
	v_or_b32_e32 v4, v4, v8
	v_lshlrev_b32_e32 v6, 8, v68
	v_lshlrev_b32_e32 v12, 8, v74
	v_lshlrev_b32_e32 v13, 8, v76
	v_lshlrev_b32_e32 v14, 8, v78
	v_lshlrev_b32_e32 v15, 8, v80
	v_lshlrev_b32_e32 v16, 8, v82
	v_lshlrev_b32_e32 v17, 8, v84
	v_lshlrev_b32_e32 v18, 8, v86
	v_lshlrev_b32_e32 v19, 8, v88
	v_lshlrev_b32_e32 v22, 8, v90
	v_add_u32_e32 v93, 0, v4
	v_and_or_b32 v4, v195, 64, v21
	v_add_u32_e32 v95, v26, v7
	v_add_u32_e32 v97, v9, v6
	v_add_u32_e32 v99, v9, v12
	v_add_u32_e32 v101, v9, v13
	v_add_u32_e32 v103, v9, v14
	v_add_u32_e32 v114, v9, v15
	v_add_u32_e32 v115, v9, v16
	v_add_u32_e32 v116, v9, v17
	v_add_u32_e32 v117, v9, v18
	v_add_u32_e32 v118, v9, v19
	v_add_u32_e32 v119, v9, v22
	v_add_u32_e32 v120, v9, v23
	v_add_u32_e32 v121, v9, v27
	v_add_u32_e32 v122, v9, v28
	v_add_u32_e32 v123, v9, v29
	v_add_u32_e32 v124, v9, v30
	v_add_u32_e32 v125, v9, v31
	v_lshlrev_b32_e32 v127, 2, v4
	s_mov_b32 s22, s2
	s_mov_b32 s98, -1
	s_branch .LBB0_399
.LBB0_398:
	s_waitcnt lgkmcnt(0)
	s_mov_b32 s98, s23
	s_mov_b32 s99, s16
	s_add_i32 s22, s22, s50
	s_cmpk_gt_i32 s22, 0x47f
	s_cbranch_scc0 .LBB0_399
	s_mul_i32 s100, s99, 0x9000
	s_ashr_i32 s101, s98, 31
	s_add_u32 s100, s100, s98
	ds_read_b128 v[162:165], v97
	s_addc_u32 s101, 0, s101
	v_mov_b32_e32 v167, s101
	v_or_b32_e32 v166, s100, v68
	v_lshlrev_b64 v[166:167], 11, v[166:167]
	v_lshl_add_u64 v[166:167], v[72:73], 0, v[166:167]
	s_waitcnt lgkmcnt(0)
	global_store_dwordx4 v[166:167], v[162:165], off nt
	ds_read_b128 v[162:165], v99
	v_mov_b32_e32 v167, s101
	v_or_b32_e32 v166, s100, v74
	v_lshlrev_b64 v[166:167], 11, v[166:167]
	v_lshl_add_u64 v[166:167], v[72:73], 0, v[166:167]
	s_waitcnt lgkmcnt(0)
	global_store_dwordx4 v[166:167], v[162:165], off nt
	ds_read_b128 v[162:165], v101
	v_mov_b32_e32 v167, s101
	v_or_b32_e32 v166, s100, v76
	v_lshlrev_b64 v[166:167], 11, v[166:167]
	v_lshl_add_u64 v[166:167], v[72:73], 0, v[166:167]
	s_waitcnt lgkmcnt(0)
	global_store_dwordx4 v[166:167], v[162:165], off nt
	ds_read_b128 v[162:165], v103
	v_mov_b32_e32 v167, s101
	v_or_b32_e32 v166, s100, v78
	v_lshlrev_b64 v[166:167], 11, v[166:167]
	v_lshl_add_u64 v[166:167], v[72:73], 0, v[166:167]
	s_waitcnt lgkmcnt(0)
	global_store_dwordx4 v[166:167], v[162:165], off nt
	ds_read_b128 v[162:165], v114
	v_mov_b32_e32 v167, s101
	v_or_b32_e32 v166, s100, v80
	v_lshlrev_b64 v[166:167], 11, v[166:167]
	v_lshl_add_u64 v[166:167], v[72:73], 0, v[166:167]
	s_waitcnt lgkmcnt(0)
	global_store_dwordx4 v[166:167], v[162:165], off nt
	ds_read_b128 v[162:165], v115
	v_mov_b32_e32 v167, s101
	v_or_b32_e32 v166, s100, v82
	v_lshlrev_b64 v[166:167], 11, v[166:167]
	v_lshl_add_u64 v[166:167], v[72:73], 0, v[166:167]
	s_waitcnt lgkmcnt(0)
	global_store_dwordx4 v[166:167], v[162:165], off nt
	ds_read_b128 v[162:165], v116
	v_mov_b32_e32 v167, s101
	v_or_b32_e32 v166, s100, v84
	v_lshlrev_b64 v[166:167], 11, v[166:167]
	v_lshl_add_u64 v[166:167], v[72:73], 0, v[166:167]
	s_waitcnt lgkmcnt(0)
	global_store_dwordx4 v[166:167], v[162:165], off nt
	ds_read_b128 v[162:165], v117
	v_mov_b32_e32 v167, s101
	v_or_b32_e32 v166, s100, v86
	v_lshlrev_b64 v[166:167], 11, v[166:167]
	v_lshl_add_u64 v[166:167], v[72:73], 0, v[166:167]
	s_waitcnt lgkmcnt(0)
	global_store_dwordx4 v[166:167], v[162:165], off nt
	ds_read_b128 v[162:165], v118
	v_mov_b32_e32 v167, s101
	v_or_b32_e32 v166, s100, v88
	v_lshlrev_b64 v[166:167], 11, v[166:167]
	v_lshl_add_u64 v[166:167], v[72:73], 0, v[166:167]
	s_waitcnt lgkmcnt(0)
	global_store_dwordx4 v[166:167], v[162:165], off nt
	ds_read_b128 v[162:165], v119
	v_mov_b32_e32 v167, s101
	v_or_b32_e32 v166, s100, v90
	v_lshlrev_b64 v[166:167], 11, v[166:167]
	v_lshl_add_u64 v[166:167], v[72:73], 0, v[166:167]
	s_waitcnt lgkmcnt(0)
	global_store_dwordx4 v[166:167], v[162:165], off nt
	ds_read_b128 v[162:165], v120
	v_mov_b32_e32 v167, s101
	v_or_b32_e32 v166, s100, v92
	v_lshlrev_b64 v[166:167], 11, v[166:167]
	v_lshl_add_u64 v[166:167], v[72:73], 0, v[166:167]
	s_waitcnt lgkmcnt(0)
	global_store_dwordx4 v[166:167], v[162:165], off nt
	ds_read_b128 v[162:165], v121
	v_mov_b32_e32 v167, s101
	v_or_b32_e32 v166, s100, v94
	v_lshlrev_b64 v[166:167], 11, v[166:167]
	v_lshl_add_u64 v[166:167], v[72:73], 0, v[166:167]
	s_waitcnt lgkmcnt(0)
	global_store_dwordx4 v[166:167], v[162:165], off nt
	ds_read_b128 v[162:165], v122
	v_mov_b32_e32 v167, s101
	v_or_b32_e32 v166, s100, v96
	v_lshlrev_b64 v[166:167], 11, v[166:167]
	v_lshl_add_u64 v[166:167], v[72:73], 0, v[166:167]
	s_waitcnt lgkmcnt(0)
	global_store_dwordx4 v[166:167], v[162:165], off nt
	ds_read_b128 v[162:165], v123
	v_mov_b32_e32 v167, s101
	v_or_b32_e32 v166, s100, v98
	v_lshlrev_b64 v[166:167], 11, v[166:167]
	v_lshl_add_u64 v[166:167], v[72:73], 0, v[166:167]
	s_waitcnt lgkmcnt(0)
	global_store_dwordx4 v[166:167], v[162:165], off nt
	ds_read_b128 v[162:165], v124
	v_mov_b32_e32 v167, s101
	v_or_b32_e32 v166, s100, v100
	v_lshlrev_b64 v[166:167], 11, v[166:167]
	v_lshl_add_u64 v[166:167], v[72:73], 0, v[166:167]
	s_waitcnt lgkmcnt(0)
	global_store_dwordx4 v[166:167], v[162:165], off nt
	ds_read_b128 v[162:165], v125
	v_mov_b32_e32 v167, s101
	v_or_b32_e32 v166, s100, v102
	v_lshlrev_b64 v[166:167], 11, v[166:167]
	v_lshl_add_u64 v[166:167], v[72:73], 0, v[166:167]
	s_waitcnt lgkmcnt(0)
	global_store_dwordx4 v[166:167], v[162:165], off nt
	s_waitcnt lgkmcnt(0)
	s_branch .LBB0_411

.LBB0_403:
	s_or_b64 exec, exec, s[6:7]
	s_cmp_eq_u32 s98, -1
	s_cbranch_scc1 .Lpa_nostore
	s_mul_i32 s100, s99, 0x9000
	s_ashr_i32 s101, s98, 31
	s_add_u32 s100, s100, s98
	ds_read_b128 v[162:165], v97
	s_addc_u32 s101, 0, s101
	v_mov_b32_e32 v167, s101
	v_or_b32_e32 v166, s100, v68
	v_lshlrev_b64 v[166:167], 11, v[166:167]
	v_lshl_add_u64 v[166:167], v[72:73], 0, v[166:167]
	s_waitcnt lgkmcnt(0)
	global_store_dwordx4 v[166:167], v[162:165], off nt
	ds_read_b128 v[162:165], v99
	v_mov_b32_e32 v167, s101
	v_or_b32_e32 v166, s100, v74
	v_lshlrev_b64 v[166:167], 11, v[166:167]
	v_lshl_add_u64 v[166:167], v[72:73], 0, v[166:167]
	s_waitcnt lgkmcnt(0)
	global_store_dwordx4 v[166:167], v[162:165], off nt
	ds_read_b128 v[162:165], v101
	v_mov_b32_e32 v167, s101
	v_or_b32_e32 v166, s100, v76
	v_lshlrev_b64 v[166:167], 11, v[166:167]
	v_lshl_add_u64 v[166:167], v[72:73], 0, v[166:167]
	s_waitcnt lgkmcnt(0)
	global_store_dwordx4 v[166:167], v[162:165], off nt
	ds_read_b128 v[162:165], v103
	v_mov_b32_e32 v167, s101
	v_or_b32_e32 v166, s100, v78
	v_lshlrev_b64 v[166:167], 11, v[166:167]
	v_lshl_add_u64 v[166:167], v[72:73], 0, v[166:167]
	s_waitcnt lgkmcnt(0)
	global_store_dwordx4 v[166:167], v[162:165], off nt
	ds_read_b128 v[162:165], v114
	v_mov_b32_e32 v167, s101
	v_or_b32_e32 v166, s100, v80
	v_lshlrev_b64 v[166:167], 11, v[166:167]
	v_lshl_add_u64 v[166:167], v[72:73], 0, v[166:167]
	s_waitcnt lgkmcnt(0)
	global_store_dwordx4 v[166:167], v[162:165], off nt
	ds_read_b128 v[162:165], v115
	v_mov_b32_e32 v167, s101
	v_or_b32_e32 v166, s100, v82
	v_lshlrev_b64 v[166:167], 11, v[166:167]
	v_lshl_add_u64 v[166:167], v[72:73], 0, v[166:167]
	s_waitcnt lgkmcnt(0)
	global_store_dwordx4 v[166:167], v[162:165], off nt
	ds_read_b128 v[162:165], v116
	v_mov_b32_e32 v167, s101
	v_or_b32_e32 v166, s100, v84
	v_lshlrev_b64 v[166:167], 11, v[166:167]
	v_lshl_add_u64 v[166:167], v[72:73], 0, v[166:167]
	s_waitcnt lgkmcnt(0)
	global_store_dwordx4 v[166:167], v[162:165], off nt
	ds_read_b128 v[162:165], v117
	v_mov_b32_e32 v167, s101
	v_or_b32_e32 v166, s100, v86
	v_lshlrev_b64 v[166:167], 11, v[166:167]
	v_lshl_add_u64 v[166:167], v[72:73], 0, v[166:167]
	s_waitcnt lgkmcnt(0)
	global_store_dwordx4 v[166:167], v[162:165], off nt
	ds_read_b128 v[162:165], v118
	v_mov_b32_e32 v167, s101
	v_or_b32_e32 v166, s100, v88
	v_lshlrev_b64 v[166:167], 11, v[166:167]
	v_lshl_add_u64 v[166:167], v[72:73], 0, v[166:167]
	s_waitcnt lgkmcnt(0)
	global_store_dwordx4 v[166:167], v[162:165], off nt
	ds_read_b128 v[162:165], v119
	v_mov_b32_e32 v167, s101
	v_or_b32_e32 v166, s100, v90
	v_lshlrev_b64 v[166:167], 11, v[166:167]
	v_lshl_add_u64 v[166:167], v[72:73], 0, v[166:167]
	s_waitcnt lgkmcnt(0)
	global_store_dwordx4 v[166:167], v[162:165], off nt
	ds_read_b128 v[162:165], v120
	v_mov_b32_e32 v167, s101
	v_or_b32_e32 v166, s100, v92
	v_lshlrev_b64 v[166:167], 11, v[166:167]
	v_lshl_add_u64 v[166:167], v[72:73], 0, v[166:167]
	s_waitcnt lgkmcnt(0)
	global_store_dwordx4 v[166:167], v[162:165], off nt
	ds_read_b128 v[162:165], v121
	v_mov_b32_e32 v167, s101
	v_or_b32_e32 v166, s100, v94
	v_lshlrev_b64 v[166:167], 11, v[166:167]
	v_lshl_add_u64 v[166:167], v[72:73], 0, v[166:167]
	s_waitcnt lgkmcnt(0)
	global_store_dwordx4 v[166:167], v[162:165], off nt
	ds_read_b128 v[162:165], v122
	v_mov_b32_e32 v167, s101
	v_or_b32_e32 v166, s100, v96
	v_lshlrev_b64 v[166:167], 11, v[166:167]
	v_lshl_add_u64 v[166:167], v[72:73], 0, v[166:167]
	s_waitcnt lgkmcnt(0)
	global_store_dwordx4 v[166:167], v[162:165], off nt
	ds_read_b128 v[162:165], v123
	v_mov_b32_e32 v167, s101
	v_or_b32_e32 v166, s100, v98
	v_lshlrev_b64 v[166:167], 11, v[166:167]
	v_lshl_add_u64 v[166:167], v[72:73], 0, v[166:167]
	s_waitcnt lgkmcnt(0)
	global_store_dwordx4 v[166:167], v[162:165], off nt
	ds_read_b128 v[162:165], v124
	v_mov_b32_e32 v167, s101
	v_or_b32_e32 v166, s100, v100
	v_lshlrev_b64 v[166:167], 11, v[166:167]
	v_lshl_add_u64 v[166:167], v[72:73], 0, v[166:167]
	s_waitcnt lgkmcnt(0)
	global_store_dwordx4 v[166:167], v[162:165], off nt
	ds_read_b128 v[162:165], v125
	v_mov_b32_e32 v167, s101
	v_or_b32_e32 v166, s100, v102
	v_lshlrev_b64 v[166:167], 11, v[166:167]
	v_lshl_add_u64 v[166:167], v[72:73], 0, v[166:167]
	s_waitcnt lgkmcnt(0)
	global_store_dwordx4 v[166:167], v[162:165], off nt
	s_waitcnt lgkmcnt(0)
.Lpa_nostore:
	s_waitcnt vmcnt(7)
	v_lshlrev_b32_e32 v40, 16, v36
	v_and_b32_e32 v41, 0xffff0000, v36
	v_lshlrev_b32_e32 v42, 16, v37
	v_and_b32_e32 v43, 0xffff0000, v37
	v_lshlrev_b32_e32 v36, 16, v38
	v_and_b32_e32 v37, 0xffff0000, v38
	v_lshlrev_b32_e32 v38, 16, v39
	v_and_b32_e32 v39, 0xffff0000, v39
	ds_write_b128 v126, v[36:39] offset:16
	s_waitcnt vmcnt(6)
	v_lshlrev_b32_e32 v36, 16, v32
	v_and_b32_e32 v37, 0xffff0000, v32
	v_lshlrev_b32_e32 v38, 16, v33
	v_and_b32_e32 v39, 0xffff0000, v33
	v_lshlrev_b32_e32 v32, 16, v34
	v_and_b32_e32 v33, 0xffff0000, v34
	v_lshlrev_b32_e32 v34, 16, v35
	v_and_b32_e32 v35, 0xffff0000, v35
	ds_write_b128 v126, v[32:35] offset:2064
	s_waitcnt vmcnt(5)
	v_lshlrev_b32_e32 v32, 16, v28
	v_and_b32_e32 v33, 0xffff0000, v28
	v_lshlrev_b32_e32 v34, 16, v29
	v_and_b32_e32 v35, 0xffff0000, v29
	v_lshlrev_b32_e32 v28, 16, v30
	v_and_b32_e32 v29, 0xffff0000, v30
	v_lshlrev_b32_e32 v30, 16, v31
	v_and_b32_e32 v31, 0xffff0000, v31
	ds_write_b128 v126, v[28:31] offset:4112
	s_waitcnt vmcnt(4)
	v_lshlrev_b32_e32 v28, 16, v24
	v_and_b32_e32 v29, 0xffff0000, v24
	v_lshlrev_b32_e32 v30, 16, v25
	v_and_b32_e32 v31, 0xffff0000, v25
	v_lshlrev_b32_e32 v24, 16, v26
	v_and_b32_e32 v25, 0xffff0000, v26
	v_lshlrev_b32_e32 v26, 16, v27
	v_and_b32_e32 v27, 0xffff0000, v27
	ds_write_b128 v126, v[24:27] offset:6160
	s_waitcnt vmcnt(3)
	v_lshlrev_b32_e32 v24, 16, v20
	v_and_b32_e32 v25, 0xffff0000, v20
	v_lshlrev_b32_e32 v26, 16, v21
	v_and_b32_e32 v27, 0xffff0000, v21
	v_lshlrev_b32_e32 v20, 16, v22
	v_and_b32_e32 v21, 0xffff0000, v22
	v_lshlrev_b32_e32 v22, 16, v23
	v_and_b32_e32 v23, 0xffff0000, v23
	ds_write_b128 v126, v[20:23] offset:8208
	s_waitcnt vmcnt(2)
	v_lshlrev_b32_e32 v20, 16, v16
	v_and_b32_e32 v21, 0xffff0000, v16
	v_lshlrev_b32_e32 v22, 16, v17
	v_and_b32_e32 v23, 0xffff0000, v17
	v_lshlrev_b32_e32 v16, 16, v18
	v_and_b32_e32 v17, 0xffff0000, v18
	v_lshlrev_b32_e32 v18, 16, v19
	v_and_b32_e32 v19, 0xffff0000, v19
	ds_write_b128 v126, v[16:19] offset:10256
	s_waitcnt vmcnt(1)
	v_lshlrev_b32_e32 v16, 16, v12
	v_and_b32_e32 v17, 0xffff0000, v12
	v_lshlrev_b32_e32 v18, 16, v13
	v_and_b32_e32 v19, 0xffff0000, v13
	v_lshlrev_b32_e32 v12, 16, v14
	v_and_b32_e32 v13, 0xffff0000, v14
	v_lshlrev_b32_e32 v14, 16, v15
	v_and_b32_e32 v15, 0xffff0000, v15
	ds_write_b128 v126, v[12:15] offset:12304
	s_waitcnt vmcnt(0)
	v_lshlrev_b32_e32 v12, 16, v8
	v_and_b32_e32 v13, 0xffff0000, v8
	v_lshlrev_b32_e32 v14, 16, v9
	v_and_b32_e32 v15, 0xffff0000, v9
	v_lshlrev_b32_e32 v8, 16, v10
	v_and_b32_e32 v9, 0xffff0000, v10
	v_lshlrev_b32_e32 v10, 16, v11
	v_and_b32_e32 v11, 0xffff0000, v11
	ds_write_b128 v126, v[40:43]
	ds_write_b128 v126, v[36:39] offset:2048
	ds_write_b128 v126, v[32:35] offset:4096
	ds_write_b128 v126, v[28:31] offset:6144
	ds_write_b128 v126, v[24:27] offset:8192
	ds_write_b128 v126, v[20:23] offset:10240
	ds_write_b128 v126, v[16:19] offset:12288
	ds_write_b128 v126, v[12:15] offset:14336
	ds_write_b128 v126, v[8:11] offset:14352
	s_and_saveexec_b64 s[6:7], vcc
	s_cbranch_execz .LBB0_405
	v_lshlrev_b32_e32 v8, 16, v4
	v_and_b32_e32 v9, 0xffff0000, v4
	v_lshlrev_b32_e32 v10, 16, v5
	v_and_b32_e32 v11, 0xffff0000, v5
	v_lshlrev_b32_e32 v4, 16, v6
	v_and_b32_e32 v5, 0xffff0000, v6
	v_lshlrev_b32_e32 v6, 16, v7
	v_and_b32_e32 v7, 0xffff0000, v7
	ds_write_b128 v126, v[8:11] offset:16384
	ds_write_b128 v126, v[4:7] offset:16400
